# stack8 plus LayerNorm wave sums by DPP row operations instead of ds_bpermute round trips
# baseline (speedup 1.0000x reference)
; __device__ __forceinline__ void ln_rows(const Ctx& C, float* y, bf16_t* xb, const float* g, const float* b, f32x2* stats, const bool write_f32) {
;     ...
;         for (int j = 0; j < 4; ++j) { v[j] = row[64 * j]; s += (v[j].x + v[j].y) + (v[j].z + v[j].w); }
;         const float mean = wave_sum(s) * (1.f / D); float s2 = 0.f;
; #pragma unroll
;         for (int j = 0; j < 4; ++j) { v[j] = v[j] - mean; s2 += (v[j].x * v[j].x + v[j].y * v[j].y) + (v[j].z * v[j].z + v[j].w * v[j].w); }
;         const float rstd = 1.f / sqrtf(wave_sum(s2) * (1.f / D) + LN_EPS);
.Lln_np2:
	v_add_f32_e32 v56, v36, v37
	v_add_f32_e32 v58, v38, v39
	v_mov_b32_e32 v53, v32
	v_mov_b32_e32 v55, v33
	v_mov_b32_e32 v57, v34
	v_mov_b32_e32 v59, v35
	v_pk_add_f32 v[52:53], v[52:53], v[54:55]
	v_pk_add_f32 v[54:55], v[56:57], v[58:59]
	s_nop 0
	v_pk_add_f32 v[52:53], v[52:53], v[54:55]
	s_nop 0
	v_add_f32_e32 v52, v52, v53
	s_nop 1
	v_add_f32_dpp v52, v52, v52 quad_perm:[1,0,3,2] row_mask:0xf bank_mask:0xf
	s_nop 1
	v_add_f32_dpp v52, v52, v52 quad_perm:[2,3,0,1] row_mask:0xf bank_mask:0xf
	s_nop 1
	v_add_f32_dpp v52, v52, v52 row_half_mirror row_mask:0xf bank_mask:0xf
	s_nop 1
	v_add_f32_dpp v52, v52, v52 row_mirror row_mask:0xf bank_mask:0xf
	s_nop 1
	v_add_f32_dpp v52, v52, v52 row_bcast:15 row_mask:0xa bank_mask:0xf
	s_nop 1
	v_add_f32_dpp v52, v52, v52 row_bcast:31 row_mask:0xc bank_mask:0xf
	s_nop 0
	v_readlane_b32 s98, v52, 63
	s_nop 1
	v_mov_b32_e32 v59, s98
	v_fmamk_f32 v57, v59, 0xba800000, v47
	v_fmamk_f32 v45, v59, 0xba800000, v45
	v_fmamk_f32 v55, v59, 0xba800000, v43
	v_fmamk_f32 v41, v59, 0xba800000, v41
	v_fmamk_f32 v56, v59, 0xba800000, v46
	v_fmac_f32_e32 v44, 0xba800000, v59
	v_mul_f32_e32 v46, v45, v45
	v_mul_f32_e32 v47, v57, v57
	v_fmamk_f32 v54, v59, 0xba800000, v42
	v_fmac_f32_e32 v40, 0xba800000, v59
	v_mul_f32_e32 v42, v41, v41
	v_mul_f32_e32 v43, v55, v55
	v_fmac_f32_e32 v46, v44, v44
	v_fmac_f32_e32 v47, v56, v56
	v_fmac_f32_e32 v42, v40, v40
	v_fmac_f32_e32 v43, v54, v54
	v_fmamk_f32 v53, v59, 0xba800000, v39
	v_fmamk_f32 v37, v59, 0xba800000, v37
	v_add_f32_e32 v46, v46, v47
	v_add_f32_e32 v42, v42, v43
	v_fmamk_f32 v52, v59, 0xba800000, v38
	v_fmac_f32_e32 v36, 0xba800000, v59
	v_mul_f32_e32 v38, v37, v37
	v_mul_f32_e32 v39, v53, v53
	v_fmamk_f32 v47, v59, 0xba800000, v35
	v_fmamk_f32 v33, v59, 0xba800000, v33
	v_add_f32_e32 v42, v46, v42
	v_fmac_f32_e32 v38, v36, v36
	v_fmac_f32_e32 v39, v52, v52
	v_fmamk_f32 v46, v59, 0xba800000, v34
	v_fmac_f32_e32 v32, 0xba800000, v59
	v_mul_f32_e32 v34, v33, v33
	v_mul_f32_e32 v35, v47, v47
	v_add_f32_e32 v38, v38, v39
	v_fmac_f32_e32 v34, v32, v32
	v_fmac_f32_e32 v35, v46, v46
	v_add_f32_e32 v38, v38, v42
	v_add_f32_e32 v34, v34, v35
	v_add_f32_e32 v34, v34, v38
	s_nop 1
	v_add_f32_dpp v34, v34, v34 quad_perm:[1,0,3,2] row_mask:0xf bank_mask:0xf
	s_nop 1
	v_add_f32_dpp v34, v34, v34 quad_perm:[2,3,0,1] row_mask:0xf bank_mask:0xf
	s_nop 1
	v_add_f32_dpp v34, v34, v34 row_half_mirror row_mask:0xf bank_mask:0xf
	s_nop 1
	v_add_f32_dpp v34, v34, v34 row_mirror row_mask:0xf bank_mask:0xf
	s_nop 1
	v_add_f32_dpp v34, v34, v34 row_bcast:15 row_mask:0xa bank_mask:0xf
	s_nop 1
	v_add_f32_dpp v34, v34, v34 row_bcast:31 row_mask:0xc bank_mask:0xf
	s_nop 0
	v_readlane_b32 s98, v34, 63
	s_nop 1
	v_mov_b32_e32 v34, s98
	v_fmamk_f32 v34, v34, 0x3a800000, v223
	v_cmp_gt_f32_e32 vcc, s10, v34
	v_mul_f32_e32 v35, 0x4f800000, v34
	s_nop 0
	v_cndmask_b32_e32 v34, v34, v35, vcc
	v_sqrt_f32_e32 v35, v34
	s_nop 0
	v_add_u32_e32 v38, -1, v35
	v_fma_f32 v39, -v38, v35, v34
	v_cmp_ge_f32_e64 s[44:45], 0, v39
	v_add_u32_e32 v39, 1, v35
	s_nop 0
	v_cndmask_b32_e64 v38, v35, v38, s[44:45]
	v_fma_f32 v35, -v39, v35, v34
	v_cmp_lt_f32_e64 s[44:45], 0, v35
	s_nop 1
	v_cndmask_b32_e64 v35, v38, v39, s[44:45]
	v_mul_f32_e32 v38, 0x37800000, v35
	v_cndmask_b32_e32 v35, v35, v38, vcc
	v_cmp_class_f32_e32 vcc, v34, v224
	s_nop 1
	v_cndmask_b32_e32 v34, v35, v34, vcc
	v_div_scale_f32 v35, s[18:19], v34, v34, 1.0
	v_rcp_f32_e32 v38, v35
	s_nop 0
	v_fma_f32 v39, -v35, v38, 1.0
	v_fmac_f32_e32 v38, v39, v38
	v_div_scale_f32 v39, vcc, 1.0, v34, 1.0
	v_mul_f32_e32 v42, v39, v38
	v_fma_f32 v43, -v35, v42, v39
	v_fmac_f32_e32 v42, v43, v38
	v_fma_f32 v35, -v35, v42, v39
	v_div_fmas_f32 v35, v35, v38, v42
	v_div_fixup_f32 v58, v35, v34, 1.0
	s_and_saveexec_b64 s[18:19], s[42:43]
	s_cbranch_execz .LBB0_387
	s_add_u32 s44, s62, s20
	v_mul_f32_e32 v34, 0x3a800000, v59
	s_addc_u32 s45, s63, s28
	v_mov_b32_e32 v35, v58
	global_store_dwordx2 v193, v[34:35], s[44:45]
